# retention epilogue: gate loads hoisted as dwords, batched row-sum butterflies, paired dword stores via DPP exchange
# speedup vs baseline: 1.0050x; 1.0050x over previous
; __device__ __forceinline__ void retention_unit(LAS unsigned char* lds, const Args& a, int b, int hh, int qb, int wid, int lane) {
;     ...
;     __syncthreads();
; #pragma unroll
;     for (int i = 0; i < 16; ++i) { const float s = rs[i] + xs[(wid ^ 1) * 32 + (i & 3) + 8 * (i >> 2) + 4 * h]; rs[i] = 1.0f / sqrtf(s * (1.0f / 256.0f) + EPS); }
.LBB0_648:
	s_or_b64 exec, exec, s[0:1]
	v_lshl_add_u32 v84, v209, 2, s80
	s_waitcnt lgkmcnt(0)
	s_barrier
	ds_read_b128 v[68:71], v84
	ds_read_b128 v[64:67], v84 offset:32
	s_movk_i32 s9, 0x1000
	s_movk_i32 s14, 0x3000
	s_mov_b32 s15, 0x9000
	s_waitcnt lgkmcnt(1)
	v_add_f32_e32 v68, v88, v68
	v_fmamk_f32 v68, v68, 0x3b800000, v204
	v_cmp_gt_f32_e32 vcc, s8, v68
	v_mul_f32_e32 v88, 0x4f800000, v68
	v_add_f32_e32 v69, v87, v69
	v_cndmask_b32_e32 v68, v68, v88, vcc
	v_sqrt_f32_e32 v88, v68
	v_fmamk_f32 v69, v69, 0x3b800000, v204
	v_mul_f32_e32 v87, 0x4f800000, v69
	v_add_f32_e32 v70, v86, v70
	v_add_u32_e32 v89, -1, v88
	v_fma_f32 v90, -v89, v88, v68
	v_cmp_ge_f32_e64 s[0:1], 0, v90
	v_add_u32_e32 v90, 1, v88
	v_fmamk_f32 v70, v70, 0x3b800000, v204
	v_cndmask_b32_e64 v89, v88, v89, s[0:1]
	v_fma_f32 v88, -v90, v88, v68
	v_cmp_lt_f32_e64 s[0:1], 0, v88
	v_mul_f32_e32 v86, 0x4f800000, v70
	v_add_f32_e32 v71, v85, v71
	v_cndmask_b32_e64 v88, v89, v90, s[0:1]
	v_mul_f32_e32 v89, 0x37800000, v88
	v_cndmask_b32_e32 v88, v88, v89, vcc
	v_cmp_class_f32_e32 vcc, v68, v205
	v_fmamk_f32 v71, v71, 0x3b800000, v204
	v_mul_f32_e32 v85, 0x4f800000, v71
	v_cndmask_b32_e32 v68, v88, v68, vcc
	v_div_scale_f32 v88, s[0:1], v68, v68, 1.0
	v_rcp_f32_e32 v89, v88
	s_waitcnt lgkmcnt(0)
	v_add_f32_e32 v64, v75, v64
	v_fmamk_f32 v64, v64, 0x3b800000, v204
	v_mul_f32_e32 v75, 0x4f800000, v64
	v_fma_f32 v90, -v88, v89, 1.0
	v_fmac_f32_e32 v89, v90, v89
	v_div_scale_f32 v90, vcc, 1.0, v68, 1.0
	v_mul_f32_e32 v91, v90, v89
	v_fma_f32 v92, -v88, v91, v90
	v_fmac_f32_e32 v91, v92, v89
	v_fma_f32 v88, -v88, v91, v90
	v_div_fmas_f32 v88, v88, v89, v91
	v_cmp_gt_f32_e32 vcc, s8, v69
	v_div_fixup_f32 v68, v88, v68, 1.0
	s_mov_b32 s22, 0xa000
	v_cndmask_b32_e32 v69, v69, v87, vcc
	v_sqrt_f32_e32 v87, v69
	s_mov_b32 s23, 0xb000
	v_mul_f32_e32 v48, v48, v68
	v_mul_f32_e32 v32, v32, v68
	v_add_u32_e32 v88, -1, v87
	v_fma_f32 v89, -v88, v87, v69
	v_cmp_ge_f32_e64 s[0:1], 0, v89
	v_add_u32_e32 v89, 1, v87
	v_mul_f32_e32 v16, v16, v68
	v_cndmask_b32_e64 v88, v87, v88, s[0:1]
	v_fma_f32 v87, -v89, v87, v69
	v_cmp_lt_f32_e64 s[0:1], 0, v87
	v_mul_f32_e32 v0, v0, v68
	s_mov_b32 s3, 0
	v_cndmask_b32_e64 v87, v88, v89, s[0:1]
	v_mul_f32_e32 v88, 0x37800000, v87
	v_cndmask_b32_e32 v87, v87, v88, vcc
	v_cmp_class_f32_e32 vcc, v69, v205
	s_nop 1
	v_cndmask_b32_e32 v69, v87, v69, vcc
	v_div_scale_f32 v87, s[0:1], v69, v69, 1.0
	v_rcp_f32_e32 v88, v87
	s_nop 0
	v_fma_f32 v89, -v87, v88, 1.0
	v_fmac_f32_e32 v88, v89, v88
	v_div_scale_f32 v89, vcc, 1.0, v69, 1.0
	v_mul_f32_e32 v90, v89, v88
	v_fma_f32 v91, -v87, v90, v89
	v_fmac_f32_e32 v90, v91, v88
	v_fma_f32 v87, -v87, v90, v89
	v_div_fmas_f32 v87, v87, v88, v90
	v_cmp_gt_f32_e32 vcc, s8, v70
	v_div_fixup_f32 v69, v87, v69, 1.0
	s_nop 0
	v_cndmask_b32_e32 v70, v70, v86, vcc
	v_sqrt_f32_e32 v86, v70
	s_nop 0
	v_add_u32_e32 v87, -1, v86
	v_fma_f32 v88, -v87, v86, v70
	v_cmp_ge_f32_e64 s[0:1], 0, v88
	v_add_u32_e32 v88, 1, v86
	s_nop 0
	v_cndmask_b32_e64 v87, v86, v87, s[0:1]
	v_fma_f32 v86, -v88, v86, v70
	v_cmp_lt_f32_e64 s[0:1], 0, v86
	s_nop 1
	v_cndmask_b32_e64 v86, v87, v88, s[0:1]
	v_mul_f32_e32 v87, 0x37800000, v86
	v_cndmask_b32_e32 v86, v86, v87, vcc
	v_cmp_class_f32_e32 vcc, v70, v205
	s_nop 1
	v_cndmask_b32_e32 v70, v86, v70, vcc
	v_div_scale_f32 v86, s[0:1], v70, v70, 1.0
	v_rcp_f32_e32 v87, v86
	s_nop 0
	v_fma_f32 v88, -v86, v87, 1.0
	v_fmac_f32_e32 v87, v88, v87
	v_div_scale_f32 v88, vcc, 1.0, v70, 1.0
	v_mul_f32_e32 v89, v88, v87
	v_fma_f32 v90, -v86, v89, v88
	v_fmac_f32_e32 v89, v90, v87
	v_fma_f32 v86, -v86, v89, v88
	v_div_fmas_f32 v86, v86, v87, v89
	v_cmp_gt_f32_e32 vcc, s8, v71
	v_div_fixup_f32 v70, v86, v70, 1.0
	s_nop 0
	v_cndmask_b32_e32 v71, v71, v85, vcc
	v_sqrt_f32_e32 v85, v71
	s_nop 0
	v_add_u32_e32 v86, -1, v85
	v_fma_f32 v87, -v86, v85, v71
	v_cmp_ge_f32_e64 s[0:1], 0, v87
	v_add_u32_e32 v87, 1, v85
	s_nop 0
	v_cndmask_b32_e64 v86, v85, v86, s[0:1]
	v_fma_f32 v85, -v87, v85, v71
	v_cmp_lt_f32_e64 s[0:1], 0, v85
	s_nop 1
	v_cndmask_b32_e64 v85, v86, v87, s[0:1]
	v_mul_f32_e32 v86, 0x37800000, v85
	v_cndmask_b32_e32 v85, v85, v86, vcc
	v_cmp_class_f32_e32 vcc, v71, v205
	s_nop 1
	v_cndmask_b32_e32 v71, v85, v71, vcc
	v_div_scale_f32 v85, s[0:1], v71, v71, 1.0
	v_rcp_f32_e32 v86, v85
	s_nop 0
	v_fma_f32 v87, -v85, v86, 1.0
	v_fmac_f32_e32 v86, v87, v86
	v_div_scale_f32 v87, vcc, 1.0, v71, 1.0
	v_mul_f32_e32 v88, v87, v86
	v_fma_f32 v89, -v85, v88, v87
	v_fmac_f32_e32 v88, v89, v86
	v_fma_f32 v85, -v85, v88, v87
	v_div_fmas_f32 v85, v85, v86, v88
	v_cmp_gt_f32_e32 vcc, s8, v64
	v_div_fixup_f32 v71, v85, v71, 1.0
	s_nop 0
	v_cndmask_b32_e32 v64, v64, v75, vcc
	v_sqrt_f32_e32 v75, v64
	s_nop 0
	v_add_u32_e32 v85, -1, v75
	v_fma_f32 v86, -v85, v75, v64
	v_cmp_ge_f32_e64 s[0:1], 0, v86
	v_add_u32_e32 v86, 1, v75
	s_nop 0
	v_cndmask_b32_e64 v85, v75, v85, s[0:1]
	v_fma_f32 v75, -v86, v75, v64
	v_cmp_lt_f32_e64 s[0:1], 0, v75
	s_nop 1
	v_cndmask_b32_e64 v75, v85, v86, s[0:1]
	v_mul_f32_e32 v85, 0x37800000, v75
	v_cndmask_b32_e32 v75, v75, v85, vcc
	v_cmp_class_f32_e32 vcc, v64, v205
	s_nop 1
	v_cndmask_b32_e32 v64, v75, v64, vcc
	v_div_scale_f32 v75, s[0:1], v64, v64, 1.0
	v_rcp_f32_e32 v85, v75
	s_nop 0
	v_fma_f32 v86, -v75, v85, 1.0
	v_fmac_f32_e32 v85, v86, v85
	v_div_scale_f32 v86, vcc, 1.0, v64, 1.0
	v_mul_f32_e32 v87, v86, v85
	v_fma_f32 v88, -v75, v87, v86
	v_fmac_f32_e32 v87, v88, v85
	v_fma_f32 v75, -v75, v87, v86
	v_div_fmas_f32 v75, v75, v85, v87
	v_div_fixup_f32 v75, v75, v64, 1.0
	v_add_f32_e32 v64, v77, v65
	v_fmamk_f32 v64, v64, 0x3b800000, v204
	v_cmp_gt_f32_e32 vcc, s8, v64
	v_mul_f32_e32 v65, 0x4f800000, v64
; __device__ __forceinline__ void retention_unit(LAS unsigned char* lds, const Args& a, int b, int hh, int qb, int wid, int lane) {
;     ...
;     for (int i = 0; i < 16; ++i) { const float s = rs[i] + xs[(wid ^ 1) * 32 + (i & 3) + 8 * (i >> 2) + 4 * h]; rs[i] = 1.0f / sqrtf(s * (1.0f / 256.0f) + EPS); }
	v_mul_f32_e32 v4, v4, v75
	v_cndmask_b32_e32 v64, v64, v65, vcc
	v_sqrt_f32_e32 v65, v64
	s_nop 0
	v_add_u32_e32 v77, -1, v65
	v_fma_f32 v85, -v77, v65, v64
	v_cmp_ge_f32_e64 s[0:1], 0, v85
	v_add_u32_e32 v85, 1, v65
	s_nop 0
	v_cndmask_b32_e64 v77, v65, v77, s[0:1]
	v_fma_f32 v65, -v85, v65, v64
	v_cmp_lt_f32_e64 s[0:1], 0, v65
	s_nop 1
	v_cndmask_b32_e64 v65, v77, v85, s[0:1]
	v_mul_f32_e32 v77, 0x37800000, v65
	v_cndmask_b32_e32 v65, v65, v77, vcc
	v_cmp_class_f32_e32 vcc, v64, v205
	s_nop 1
	v_cndmask_b32_e32 v64, v65, v64, vcc
	v_div_scale_f32 v65, s[0:1], v64, v64, 1.0
	v_rcp_f32_e32 v77, v65
	s_nop 0
	v_fma_f32 v85, -v65, v77, 1.0
	v_fmac_f32_e32 v77, v85, v77
	v_div_scale_f32 v85, vcc, 1.0, v64, 1.0
	v_mul_f32_e32 v86, v85, v77
	v_fma_f32 v87, -v65, v86, v85
	v_fmac_f32_e32 v86, v87, v77
	v_fma_f32 v65, -v65, v86, v85
	v_div_fmas_f32 v65, v65, v77, v86
	v_div_fixup_f32 v77, v65, v64, 1.0
	v_add_f32_e32 v64, v79, v66
	v_fmamk_f32 v64, v64, 0x3b800000, v204
	v_cmp_gt_f32_e32 vcc, s8, v64
	v_mul_f32_e32 v65, 0x4f800000, v64
	s_nop 0
	v_cndmask_b32_e32 v64, v64, v65, vcc
	v_sqrt_f32_e32 v65, v64
	s_nop 0
	v_add_u32_e32 v66, -1, v65
	v_fma_f32 v79, -v66, v65, v64
	v_cmp_ge_f32_e64 s[0:1], 0, v79
	v_add_u32_e32 v79, 1, v65
	s_nop 0
	v_cndmask_b32_e64 v66, v65, v66, s[0:1]
	v_fma_f32 v65, -v79, v65, v64
	v_cmp_lt_f32_e64 s[0:1], 0, v65
	s_nop 1
	v_cndmask_b32_e64 v65, v66, v79, s[0:1]
	v_mul_f32_e32 v66, 0x37800000, v65
	v_cndmask_b32_e32 v65, v65, v66, vcc
	v_cmp_class_f32_e32 vcc, v64, v205
	s_nop 1
	v_cndmask_b32_e32 v64, v65, v64, vcc
	v_div_scale_f32 v65, s[0:1], v64, v64, 1.0
	v_rcp_f32_e32 v66, v65
	s_nop 0
	v_fma_f32 v79, -v65, v66, 1.0
	v_fmac_f32_e32 v66, v79, v66
	v_div_scale_f32 v79, vcc, 1.0, v64, 1.0
	v_mul_f32_e32 v85, v79, v66
	v_fma_f32 v86, -v65, v85, v79
	v_fmac_f32_e32 v85, v86, v66
	v_fma_f32 v65, -v65, v85, v79
	v_div_fmas_f32 v65, v65, v66, v85
	v_div_fixup_f32 v79, v65, v64, 1.0
	v_add_f32_e32 v64, v81, v67
	v_fmamk_f32 v64, v64, 0x3b800000, v204
	v_cmp_gt_f32_e32 vcc, s8, v64
	v_mul_f32_e32 v65, 0x4f800000, v64
	s_nop 0
	v_cndmask_b32_e32 v64, v64, v65, vcc
	v_sqrt_f32_e32 v65, v64
	s_nop 0
	v_add_u32_e32 v66, -1, v65
	v_fma_f32 v67, -v66, v65, v64
	v_cmp_ge_f32_e64 s[0:1], 0, v67
	v_add_u32_e32 v67, 1, v65
	s_nop 0
	v_cndmask_b32_e64 v66, v65, v66, s[0:1]
	v_fma_f32 v65, -v67, v65, v64
	v_cmp_lt_f32_e64 s[0:1], 0, v65
	s_nop 1
	v_cndmask_b32_e64 v65, v66, v67, s[0:1]
	v_mul_f32_e32 v66, 0x37800000, v65
	v_cndmask_b32_e32 v65, v65, v66, vcc
	v_cmp_class_f32_e32 vcc, v64, v205
	s_nop 1
	v_cndmask_b32_e32 v64, v65, v64, vcc
	v_div_scale_f32 v65, s[0:1], v64, v64, 1.0
	v_rcp_f32_e32 v66, v65
	s_nop 0
	v_fma_f32 v67, -v65, v66, 1.0
	v_fmac_f32_e32 v66, v67, v66
	v_div_scale_f32 v67, vcc, 1.0, v64, 1.0
	v_mul_f32_e32 v81, v67, v66
	v_fma_f32 v85, -v65, v81, v67
	v_fmac_f32_e32 v81, v85, v66
	v_fma_f32 v65, -v65, v81, v67
	v_div_fmas_f32 v65, v65, v66, v81
	v_div_fixup_f32 v81, v65, v64, 1.0
	ds_read_b128 v[64:67], v84 offset:64
	s_waitcnt lgkmcnt(0)
	v_add_f32_e32 v64, v72, v64
	v_fmamk_f32 v64, v64, 0x3b800000, v204
	v_cmp_gt_f32_e32 vcc, s8, v64
	v_mul_f32_e32 v72, 0x4f800000, v64
	s_nop 0
	v_cndmask_b32_e32 v64, v64, v72, vcc
	v_sqrt_f32_e32 v72, v64
	s_nop 0
	v_add_u32_e32 v85, -1, v72
	v_fma_f32 v86, -v85, v72, v64
	v_cmp_ge_f32_e64 s[0:1], 0, v86
	v_add_u32_e32 v86, 1, v72
	s_nop 0
	v_cndmask_b32_e64 v85, v72, v85, s[0:1]
	v_fma_f32 v72, -v86, v72, v64
	v_cmp_lt_f32_e64 s[0:1], 0, v72
	s_nop 1
	v_cndmask_b32_e64 v72, v85, v86, s[0:1]
	v_mul_f32_e32 v85, 0x37800000, v72
	v_cndmask_b32_e32 v72, v72, v85, vcc
	v_cmp_class_f32_e32 vcc, v64, v205
	s_nop 1
	v_cndmask_b32_e32 v64, v72, v64, vcc
	v_div_scale_f32 v72, s[0:1], v64, v64, 1.0
	v_rcp_f32_e32 v85, v72
	s_nop 0
	v_fma_f32 v86, -v72, v85, 1.0
	v_fmac_f32_e32 v85, v86, v85
	v_div_scale_f32 v86, vcc, 1.0, v64, 1.0
	v_mul_f32_e32 v87, v86, v85
	v_fma_f32 v88, -v72, v87, v86
	v_fmac_f32_e32 v87, v88, v85
	v_fma_f32 v72, -v72, v87, v86
	v_div_fmas_f32 v72, v72, v85, v87
	v_div_fixup_f32 v72, v72, v64, 1.0
	v_add_f32_e32 v64, v73, v65
	v_fmamk_f32 v64, v64, 0x3b800000, v204
	v_cmp_gt_f32_e32 vcc, s8, v64
	v_mul_f32_e32 v65, 0x4f800000, v64
	s_nop 0
	v_cndmask_b32_e32 v64, v64, v65, vcc
	v_sqrt_f32_e32 v65, v64
	s_nop 0
	v_add_u32_e32 v73, -1, v65
	v_fma_f32 v85, -v73, v65, v64
	v_cmp_ge_f32_e64 s[0:1], 0, v85
	v_add_u32_e32 v85, 1, v65
	s_nop 0
	v_cndmask_b32_e64 v73, v65, v73, s[0:1]
	v_fma_f32 v65, -v85, v65, v64
	v_cmp_lt_f32_e64 s[0:1], 0, v65
	s_nop 1
	v_cndmask_b32_e64 v65, v73, v85, s[0:1]
	v_mul_f32_e32 v73, 0x37800000, v65
	v_cndmask_b32_e32 v65, v65, v73, vcc
	v_cmp_class_f32_e32 vcc, v64, v205
	s_nop 1
	v_cndmask_b32_e32 v64, v65, v64, vcc
	v_div_scale_f32 v65, s[0:1], v64, v64, 1.0
	v_rcp_f32_e32 v73, v65
	s_nop 0
	v_fma_f32 v85, -v65, v73, 1.0
	v_fmac_f32_e32 v73, v85, v73
	v_div_scale_f32 v85, vcc, 1.0, v64, 1.0
	v_mul_f32_e32 v86, v85, v73
	v_fma_f32 v87, -v65, v86, v85
	v_fmac_f32_e32 v86, v87, v73
	v_fma_f32 v65, -v65, v86, v85
	v_div_fmas_f32 v65, v65, v73, v86
	v_div_fixup_f32 v73, v65, v64, 1.0
	v_add_f32_e32 v64, v74, v66
	v_fmamk_f32 v64, v64, 0x3b800000, v204
	v_cmp_gt_f32_e32 vcc, s8, v64
	v_mul_f32_e32 v65, 0x4f800000, v64
	s_nop 0
	v_cndmask_b32_e32 v64, v64, v65, vcc
	v_sqrt_f32_e32 v65, v64
	s_nop 0
	v_add_u32_e32 v66, -1, v65
	v_fma_f32 v74, -v66, v65, v64
	v_cmp_ge_f32_e64 s[0:1], 0, v74
	v_add_u32_e32 v74, 1, v65
	s_nop 0
	v_cndmask_b32_e64 v66, v65, v66, s[0:1]
	v_fma_f32 v65, -v74, v65, v64
	v_cmp_lt_f32_e64 s[0:1], 0, v65
	s_nop 1
	v_cndmask_b32_e64 v65, v66, v74, s[0:1]
	v_mul_f32_e32 v66, 0x37800000, v65
	v_cndmask_b32_e32 v65, v65, v66, vcc
; __device__ __forceinline__ unsigned cvtpk(float lo, float hi) { f32x2 v = {lo, hi}; bf16x2_t b = __builtin_convertvector(v, bf16x2_t); return __builtin_bit_cast(unsigned, b); }
; __device__ __forceinline__ float bf2f(bf16_t b) { return __uint_as_float(((unsigned)b) << 16); }
; __device__ __forceinline__ void retention_unit(LAS unsigned char* lds, const Args& a, int b, int hh, int qb, int wid, int lane) {
;     ...
;     for (int i = 0; i < 16; ++i) { const float s = rs[i] + xs[(wid ^ 1) * 32 + (i & 3) + 8 * (i >> 2) + 4 * h]; rs[i] = 1.0f / sqrtf(s * (1.0f / 256.0f) + EPS); }
;     const size_t obase = (size_t)(b * SEQ + qb * 128 + rg * 32 + 4 * h) * DM + hh * 256 + hf * 128 + r;
; #pragma unroll
;     for (int hh2 = 0; hh2 < 2; ++hh2) {
;         bf16_t gv[8][4];
; #pragma unroll
;         for (int ii = 0; ii < 8; ++ii) { const int i = hh2 * 8 + ii; const size_t off = obase + (size_t)((i & 3) + 8 * (i >> 2)) * DM;
; #pragma unroll
;             for (int d = 0; d < 4; ++d) gv[ii][d] = Gp[off + 32 * d]; }
;         asm volatile("" ::: "memory");
; #pragma unroll
;         for (int ii = 0; ii < 8; ++ii) { const int i = hh2 * 8 + ii; const size_t off = obase + (size_t)((i & 3) + 8 * (i >> 2)) * DM;
; #pragma unroll
;             for (int d = 0; d < 4; ++d) Qp[off + 32 * d] = (bf16_t)(cvtpk(O[d][i] * rs[i] * bf2f(gv[ii][d]), 0.f) & 0xffffu); }
	v_cmp_class_f32_e32 vcc, v64, v205
	s_nop 1
	v_cndmask_b32_e32 v64, v65, v64, vcc
	v_div_scale_f32 v65, s[0:1], v64, v64, 1.0
	v_rcp_f32_e32 v66, v65
	s_nop 0
	v_fma_f32 v74, -v65, v66, 1.0
	v_fmac_f32_e32 v66, v74, v66
	v_div_scale_f32 v74, vcc, 1.0, v64, 1.0
	v_mul_f32_e32 v85, v74, v66
	v_fma_f32 v86, -v65, v85, v74
	v_fmac_f32_e32 v85, v86, v66
	v_fma_f32 v65, -v65, v85, v74
	v_div_fmas_f32 v65, v65, v66, v85
	v_div_fixup_f32 v74, v65, v64, 1.0
	v_add_f32_e32 v64, v76, v67
	v_fmamk_f32 v64, v64, 0x3b800000, v204
	v_cmp_gt_f32_e32 vcc, s8, v64
	v_mul_f32_e32 v65, 0x4f800000, v64
	s_nop 0
	v_cndmask_b32_e32 v64, v64, v65, vcc
	v_sqrt_f32_e32 v65, v64
	s_nop 0
	v_add_u32_e32 v66, -1, v65
	v_fma_f32 v67, -v66, v65, v64
	v_cmp_ge_f32_e64 s[0:1], 0, v67
	v_add_u32_e32 v67, 1, v65
	s_nop 0
	v_cndmask_b32_e64 v66, v65, v66, s[0:1]
	v_fma_f32 v65, -v67, v65, v64
	v_cmp_lt_f32_e64 s[0:1], 0, v65
	s_nop 1
	v_cndmask_b32_e64 v65, v66, v67, s[0:1]
	v_mul_f32_e32 v66, 0x37800000, v65
	v_cndmask_b32_e32 v65, v65, v66, vcc
	v_cmp_class_f32_e32 vcc, v64, v205
	s_nop 1
	v_cndmask_b32_e32 v64, v65, v64, vcc
	v_div_scale_f32 v65, s[0:1], v64, v64, 1.0
	v_rcp_f32_e32 v66, v65
	s_nop 0
	v_fma_f32 v67, -v65, v66, 1.0
	v_fmac_f32_e32 v66, v67, v66
	v_div_scale_f32 v67, vcc, 1.0, v64, 1.0
	v_mul_f32_e32 v76, v67, v66
	v_fma_f32 v85, -v65, v76, v67
	v_fmac_f32_e32 v76, v85, v66
	v_fma_f32 v65, -v65, v76, v67
	v_div_fmas_f32 v65, v65, v66, v76
	v_div_fixup_f32 v76, v65, v64, 1.0
	ds_read_b128 v[64:67], v84 offset:96
	s_waitcnt lgkmcnt(0)
	v_add_f32_e32 v64, v83, v64
	v_fmamk_f32 v64, v64, 0x3b800000, v204
	v_cmp_gt_f32_e32 vcc, s8, v64
	v_mul_f32_e32 v83, 0x4f800000, v64
	s_nop 0
	v_cndmask_b32_e32 v64, v64, v83, vcc
	v_sqrt_f32_e32 v83, v64
	s_nop 0
	v_add_u32_e32 v84, -1, v83
	v_fma_f32 v85, -v84, v83, v64
	v_cmp_ge_f32_e64 s[0:1], 0, v85
	v_add_u32_e32 v85, 1, v83
	s_nop 0
	v_cndmask_b32_e64 v84, v83, v84, s[0:1]
	v_fma_f32 v83, -v85, v83, v64
	v_cmp_lt_f32_e64 s[0:1], 0, v83
	s_nop 1
	v_cndmask_b32_e64 v83, v84, v85, s[0:1]
	v_mul_f32_e32 v84, 0x37800000, v83
	v_cndmask_b32_e32 v83, v83, v84, vcc
	v_cmp_class_f32_e32 vcc, v64, v205
	s_nop 1
	v_cndmask_b32_e32 v64, v83, v64, vcc
	v_div_scale_f32 v83, s[0:1], v64, v64, 1.0
	v_rcp_f32_e32 v84, v83
	s_nop 0
	v_fma_f32 v85, -v83, v84, 1.0
	v_fmac_f32_e32 v84, v85, v84
	v_div_scale_f32 v85, vcc, 1.0, v64, 1.0
	v_mul_f32_e32 v86, v85, v84
	v_fma_f32 v87, -v83, v86, v85
	v_fmac_f32_e32 v86, v87, v84
	v_fma_f32 v83, -v83, v86, v85
	v_div_fmas_f32 v83, v83, v84, v86
	v_div_fixup_f32 v83, v83, v64, 1.0
	v_add_f32_e32 v64, v82, v65
	v_fmamk_f32 v64, v64, 0x3b800000, v204
	v_cmp_gt_f32_e32 vcc, s8, v64
	v_mul_f32_e32 v65, 0x4f800000, v64
	s_nop 0
	v_cndmask_b32_e32 v64, v64, v65, vcc
	v_sqrt_f32_e32 v65, v64
	s_nop 0
	v_add_u32_e32 v82, -1, v65
	v_fma_f32 v84, -v82, v65, v64
	v_cmp_ge_f32_e64 s[0:1], 0, v84
	v_add_u32_e32 v84, 1, v65
	s_nop 0
	v_cndmask_b32_e64 v82, v65, v82, s[0:1]
	v_fma_f32 v65, -v84, v65, v64
	v_cmp_lt_f32_e64 s[0:1], 0, v65
	s_nop 1
	v_cndmask_b32_e64 v65, v82, v84, s[0:1]
	v_mul_f32_e32 v82, 0x37800000, v65
	v_cndmask_b32_e32 v65, v65, v82, vcc
	v_cmp_class_f32_e32 vcc, v64, v205
	s_nop 1
	v_cndmask_b32_e32 v64, v65, v64, vcc
	v_div_scale_f32 v65, s[0:1], v64, v64, 1.0
	v_rcp_f32_e32 v82, v65
	s_nop 0
	v_fma_f32 v84, -v65, v82, 1.0
	v_fmac_f32_e32 v82, v84, v82
	v_div_scale_f32 v84, vcc, 1.0, v64, 1.0
	v_mul_f32_e32 v85, v84, v82
	v_fma_f32 v86, -v65, v85, v84
	v_fmac_f32_e32 v85, v86, v82
	v_fma_f32 v65, -v65, v85, v84
	v_div_fmas_f32 v65, v65, v82, v85
	v_div_fixup_f32 v82, v65, v64, 1.0
	v_add_f32_e32 v64, v80, v66
	v_fmamk_f32 v64, v64, 0x3b800000, v204
	v_cmp_gt_f32_e32 vcc, s8, v64
	v_mul_f32_e32 v65, 0x4f800000, v64
	s_nop 0
	v_cndmask_b32_e32 v64, v64, v65, vcc
	v_sqrt_f32_e32 v65, v64
	s_nop 0
	v_add_u32_e32 v66, -1, v65
	v_fma_f32 v80, -v66, v65, v64
	v_cmp_ge_f32_e64 s[0:1], 0, v80
	v_add_u32_e32 v80, 1, v65
	s_nop 0
	v_cndmask_b32_e64 v66, v65, v66, s[0:1]
	v_fma_f32 v65, -v80, v65, v64
	v_cmp_lt_f32_e64 s[0:1], 0, v65
	s_nop 1
	v_cndmask_b32_e64 v65, v66, v80, s[0:1]
	v_mul_f32_e32 v66, 0x37800000, v65
	v_cndmask_b32_e32 v65, v65, v66, vcc
	v_cmp_class_f32_e32 vcc, v64, v205
	s_nop 1
	v_cndmask_b32_e32 v64, v65, v64, vcc
	v_div_scale_f32 v65, s[0:1], v64, v64, 1.0
	v_rcp_f32_e32 v66, v65
	s_nop 0
	v_fma_f32 v80, -v65, v66, 1.0
	v_fmac_f32_e32 v66, v80, v66
	v_div_scale_f32 v80, vcc, 1.0, v64, 1.0
	v_mul_f32_e32 v84, v80, v66
	v_fma_f32 v85, -v65, v84, v80
	v_fmac_f32_e32 v84, v85, v66
	v_fma_f32 v65, -v65, v84, v80
	v_div_fmas_f32 v65, v65, v66, v84
	v_div_fixup_f32 v80, v65, v64, 1.0
	v_add_f32_e32 v64, v78, v67
	v_fmamk_f32 v64, v64, 0x3b800000, v204
	v_cmp_gt_f32_e32 vcc, s8, v64
	v_mul_f32_e32 v65, 0x4f800000, v64
	s_nop 0
	v_cndmask_b32_e32 v64, v64, v65, vcc
	v_sqrt_f32_e32 v65, v64
	s_nop 0
	v_add_u32_e32 v66, -1, v65
	v_fma_f32 v67, -v66, v65, v64
	v_cmp_ge_f32_e64 s[0:1], 0, v67
	v_add_u32_e32 v67, 1, v65
	s_nop 0
	v_cndmask_b32_e64 v66, v65, v66, s[0:1]
	v_fma_f32 v65, -v67, v65, v64
	v_cmp_lt_f32_e64 s[0:1], 0, v65
	s_nop 1
	v_cndmask_b32_e64 v65, v66, v67, s[0:1]
	v_mul_f32_e32 v66, 0x37800000, v65
	v_cndmask_b32_e32 v65, v65, v66, vcc
	v_cmp_class_f32_e32 vcc, v64, v205
	s_nop 1
	v_cndmask_b32_e32 v64, v65, v64, vcc
	v_div_scale_f32 v65, s[0:1], v64, v64, 1.0
	v_rcp_f32_e32 v66, v65
	s_add_i32 s0, s42, s41
	v_fma_f32 v67, -v65, v66, 1.0
	v_fmac_f32_e32 v66, v67, v66
	v_div_scale_f32 v67, vcc, 1.0, v64, 1.0
	v_mul_f32_e32 v78, v67, v66
	v_fma_f32 v84, -v65, v78, v67
	v_fmac_f32_e32 v78, v84, v66
	v_fma_f32 v65, -v65, v78, v67
	v_div_fmas_f32 v65, v65, v66, v78
	v_div_fixup_f32 v78, v65, v64, 1.0
	v_add_u32_e32 v64, s0, v209
	v_ashrrev_i32_e32 v65, 31, v64
	v_lshlrev_b64 v[64:65], 11, v[64:65]
	v_lshl_add_u64 v[64:65], v[64:65], 0, s[46:47]
	v_or_b32_e32 v64, s78, v64
	v_or_b32_e32 v64, v64, v208
	v_readlane_b32 s0, v242, 30
	v_lshlrev_b64 v[64:65], 1, v[64:65]
	v_readlane_b32 s1, v242, 31
	s_nop 1
	v_lshl_add_u64 v[66:67], s[0:1], 0, v[64:65]
	v_lshl_add_u64 v[64:65], s[12:13], 0, v[64:65]
	v_and_b32_e32 v216, 1, v208
	v_cmp_eq_u32_e64 s[14:15], 0, v216
	v_mul_u32_u24_e32 v216, 62, v216
	v_mov_b32_e32 v217, 0
	s_movk_i32 s0, 0x1000
	s_mov_b32 s1, 0
	s_movk_i32 s22, 0x5000
	s_mov_b32 s23, 0
	v_lshl_add_u64 v[210:211], v[64:65], 0, v[216:217]
	s_waitcnt vmcnt(0)
; __device__ __forceinline__ unsigned cvtpk(float lo, float hi) { f32x2 v = {lo, hi}; bf16x2_t b = __builtin_convertvector(v, bf16x2_t); return __builtin_bit_cast(unsigned, b); }
; __device__ __forceinline__ float bf2f(bf16_t b) { return __uint_as_float(((unsigned)b) << 16); }
; __device__ __forceinline__ void retention_unit(LAS unsigned char* lds, const Args& a, int b, int hh, int qb, int wid, int lane) {
;     ...
;         for (int ii = 0; ii < 8; ++ii) { const int i = hh2 * 8 + ii; const size_t off = obase + (size_t)((i & 3) + 8 * (i >> 2)) * DM;
; #pragma unroll
;             for (int d = 0; d < 4; ++d) Qp[off + 32 * d] = (bf16_t)(cvtpk(O[d][i] * rs[i] * bf2f(gv[ii][d]), 0.f) & 0xffffu); }
	v_cndmask_b32_e64 v218, v48, v32, s[14:15]
	v_cndmask_b32_e64 v219, v16, v0, s[14:15]
	v_lshlrev_b32_e32 v234, 16, v128
	v_and_b32_e32 v238, 0xffff0000, v128
	v_lshlrev_b32_e32 v235, 16, v129
	v_and_b32_e32 v239, 0xffff0000, v129
	v_mov_b32_dpp v222, v218 quad_perm:[1,0,3,2] row_mask:0xf bank_mask:0xf
	v_mov_b32_dpp v223, v219 quad_perm:[1,0,3,2] row_mask:0xf bank_mask:0xf
	v_cndmask_b32_e64 v226, v222, v48, s[14:15]
	v_cndmask_b32_e64 v230, v32, v222, s[14:15]
	v_cndmask_b32_e64 v227, v223, v16, s[14:15]
	v_cndmask_b32_e64 v231, v0, v223, s[14:15]
	v_mul_f32_e32 v226, v226, v234
	v_mul_f32_e32 v230, v230, v238
	v_mul_f32_e32 v227, v227, v235
	v_mul_f32_e32 v231, v231, v239
	v_cvt_pk_bf16_f32 v226, v226, v230
	v_cvt_pk_bf16_f32 v227, v227, v231
	global_store_dword v[210:211], v226, off
	global_store_dword v[210:211], v227, off offset:128
	v_lshl_add_u64 v[214:215], v[210:211], 0, s[0:1]
	v_mul_f32_e32 v49, v49, v69
	v_mul_f32_e32 v33, v33, v69
	v_mul_f32_e32 v17, v17, v69
	v_mul_f32_e32 v1, v1, v69
	v_cndmask_b32_e64 v220, v49, v33, s[14:15]
	v_cndmask_b32_e64 v221, v17, v1, s[14:15]
	v_lshlrev_b32_e32 v236, 16, v130
	v_and_b32_e32 v240, 0xffff0000, v130
	v_lshlrev_b32_e32 v237, 16, v131
	v_and_b32_e32 v241, 0xffff0000, v131
	v_mov_b32_dpp v224, v220 quad_perm:[1,0,3,2] row_mask:0xf bank_mask:0xf
	v_mov_b32_dpp v225, v221 quad_perm:[1,0,3,2] row_mask:0xf bank_mask:0xf
	v_cndmask_b32_e64 v228, v224, v49, s[14:15]
	v_cndmask_b32_e64 v232, v33, v224, s[14:15]
	v_cndmask_b32_e64 v229, v225, v17, s[14:15]
	v_cndmask_b32_e64 v233, v1, v225, s[14:15]
	v_mul_f32_e32 v228, v228, v236
	v_mul_f32_e32 v232, v232, v240
	v_mul_f32_e32 v229, v229, v237
	v_mul_f32_e32 v233, v233, v241
	v_cvt_pk_bf16_f32 v228, v228, v232
	v_cvt_pk_bf16_f32 v229, v229, v233
	global_store_dword v[214:215], v228, off
	global_store_dword v[214:215], v229, off offset:128
	v_lshl_add_u64 v[212:213], v[214:215], 0, s[0:1]
	v_mul_f32_e32 v50, v50, v70
	v_mul_f32_e32 v34, v34, v70
	v_mul_f32_e32 v18, v18, v70
	v_mul_f32_e32 v2, v2, v70
	v_cndmask_b32_e64 v218, v50, v34, s[14:15]
	v_cndmask_b32_e64 v219, v18, v2, s[14:15]
	v_lshlrev_b32_e32 v234, 16, v132
	v_and_b32_e32 v238, 0xffff0000, v132
	v_lshlrev_b32_e32 v235, 16, v133
	v_and_b32_e32 v239, 0xffff0000, v133
	v_mov_b32_dpp v222, v218 quad_perm:[1,0,3,2] row_mask:0xf bank_mask:0xf
	v_mov_b32_dpp v223, v219 quad_perm:[1,0,3,2] row_mask:0xf bank_mask:0xf
	v_cndmask_b32_e64 v226, v222, v50, s[14:15]
	v_cndmask_b32_e64 v230, v34, v222, s[14:15]
	v_cndmask_b32_e64 v227, v223, v18, s[14:15]
	v_cndmask_b32_e64 v231, v2, v223, s[14:15]
	v_mul_f32_e32 v226, v226, v234
	v_mul_f32_e32 v230, v230, v238
	v_mul_f32_e32 v227, v227, v235
	v_mul_f32_e32 v231, v231, v239
	v_cvt_pk_bf16_f32 v226, v226, v230
	v_cvt_pk_bf16_f32 v227, v227, v231
	global_store_dword v[212:213], v226, off
	global_store_dword v[212:213], v227, off offset:128
	v_lshl_add_u64 v[214:215], v[212:213], 0, s[0:1]
	v_mul_f32_e32 v51, v51, v71
	v_mul_f32_e32 v35, v35, v71
	v_mul_f32_e32 v19, v19, v71
	v_mul_f32_e32 v3, v3, v71
	v_cndmask_b32_e64 v220, v51, v35, s[14:15]
	v_cndmask_b32_e64 v221, v19, v3, s[14:15]
	v_lshlrev_b32_e32 v236, 16, v134
	v_and_b32_e32 v240, 0xffff0000, v134
	v_lshlrev_b32_e32 v237, 16, v135
	v_and_b32_e32 v241, 0xffff0000, v135
	v_mov_b32_dpp v224, v220 quad_perm:[1,0,3,2] row_mask:0xf bank_mask:0xf
	v_mov_b32_dpp v225, v221 quad_perm:[1,0,3,2] row_mask:0xf bank_mask:0xf
	v_cndmask_b32_e64 v228, v224, v51, s[14:15]
	v_cndmask_b32_e64 v232, v35, v224, s[14:15]
	v_cndmask_b32_e64 v229, v225, v19, s[14:15]
	v_cndmask_b32_e64 v233, v3, v225, s[14:15]
	v_mul_f32_e32 v228, v228, v236
	v_mul_f32_e32 v232, v232, v240
	v_mul_f32_e32 v229, v229, v237
	v_mul_f32_e32 v233, v233, v241
	v_cvt_pk_bf16_f32 v228, v228, v232
	v_cvt_pk_bf16_f32 v229, v229, v233
	global_store_dword v[214:215], v228, off
	global_store_dword v[214:215], v229, off offset:128
	v_lshl_add_u64 v[212:213], v[214:215], 0, s[22:23]
	v_mul_f32_e32 v52, v52, v75
	v_mul_f32_e32 v36, v36, v75
	v_mul_f32_e32 v20, v20, v75
	v_cndmask_b32_e64 v218, v52, v36, s[14:15]
	v_cndmask_b32_e64 v219, v20, v4, s[14:15]
	v_lshlrev_b32_e32 v234, 16, v136
	v_and_b32_e32 v238, 0xffff0000, v136
	v_lshlrev_b32_e32 v235, 16, v137
	v_and_b32_e32 v239, 0xffff0000, v137
	v_mov_b32_dpp v222, v218 quad_perm:[1,0,3,2] row_mask:0xf bank_mask:0xf
	v_mov_b32_dpp v223, v219 quad_perm:[1,0,3,2] row_mask:0xf bank_mask:0xf
	v_cndmask_b32_e64 v226, v222, v52, s[14:15]
	v_cndmask_b32_e64 v230, v36, v222, s[14:15]
	v_cndmask_b32_e64 v227, v223, v20, s[14:15]
	v_cndmask_b32_e64 v231, v4, v223, s[14:15]
	v_mul_f32_e32 v226, v226, v234
	v_mul_f32_e32 v230, v230, v238
	v_mul_f32_e32 v227, v227, v235
	v_mul_f32_e32 v231, v231, v239
	v_cvt_pk_bf16_f32 v226, v226, v230
	v_cvt_pk_bf16_f32 v227, v227, v231
	global_store_dword v[212:213], v226, off
	global_store_dword v[212:213], v227, off offset:128
	v_lshl_add_u64 v[214:215], v[212:213], 0, s[0:1]
	v_mul_f32_e32 v53, v53, v77
	v_mul_f32_e32 v37, v37, v77
	v_mul_f32_e32 v21, v21, v77
	v_mul_f32_e32 v5, v5, v77
	v_cndmask_b32_e64 v220, v53, v37, s[14:15]
	v_cndmask_b32_e64 v221, v21, v5, s[14:15]
	v_lshlrev_b32_e32 v236, 16, v138
	v_and_b32_e32 v240, 0xffff0000, v138
	v_lshlrev_b32_e32 v237, 16, v139
	v_and_b32_e32 v241, 0xffff0000, v139
	v_mov_b32_dpp v224, v220 quad_perm:[1,0,3,2] row_mask:0xf bank_mask:0xf
	v_mov_b32_dpp v225, v221 quad_perm:[1,0,3,2] row_mask:0xf bank_mask:0xf
	v_cndmask_b32_e64 v228, v224, v53, s[14:15]
	v_cndmask_b32_e64 v232, v37, v224, s[14:15]
	v_cndmask_b32_e64 v229, v225, v21, s[14:15]
	v_cndmask_b32_e64 v233, v5, v225, s[14:15]
	v_mul_f32_e32 v228, v228, v236
; __device__ __forceinline__ unsigned cvtpk(float lo, float hi) { f32x2 v = {lo, hi}; bf16x2_t b = __builtin_convertvector(v, bf16x2_t); return __builtin_bit_cast(unsigned, b); }
; __device__ __forceinline__ float bf2f(bf16_t b) { return __uint_as_float(((unsigned)b) << 16); }
; __device__ __forceinline__ void retention_unit(LAS unsigned char* lds, const Args& a, int b, int hh, int qb, int wid, int lane) {
;     ...
;         for (int ii = 0; ii < 8; ++ii) { const int i = hh2 * 8 + ii; const size_t off = obase + (size_t)((i & 3) + 8 * (i >> 2)) * DM;
; #pragma unroll
;             for (int d = 0; d < 4; ++d) Qp[off + 32 * d] = (bf16_t)(cvtpk(O[d][i] * rs[i] * bf2f(gv[ii][d]), 0.f) & 0xffffu); }
	v_mul_f32_e32 v232, v232, v240
	v_mul_f32_e32 v229, v229, v237
	v_mul_f32_e32 v233, v233, v241
	v_cvt_pk_bf16_f32 v228, v228, v232
	v_cvt_pk_bf16_f32 v229, v229, v233
	global_store_dword v[214:215], v228, off
	global_store_dword v[214:215], v229, off offset:128
	v_lshl_add_u64 v[212:213], v[214:215], 0, s[0:1]
	v_mul_f32_e32 v54, v54, v79
	v_mul_f32_e32 v38, v38, v79
	v_mul_f32_e32 v22, v22, v79
	v_mul_f32_e32 v6, v6, v79
	v_cndmask_b32_e64 v218, v54, v38, s[14:15]
	v_cndmask_b32_e64 v219, v22, v6, s[14:15]
	v_lshlrev_b32_e32 v234, 16, v140
	v_and_b32_e32 v238, 0xffff0000, v140
	v_lshlrev_b32_e32 v235, 16, v141
	v_and_b32_e32 v239, 0xffff0000, v141
	v_mov_b32_dpp v222, v218 quad_perm:[1,0,3,2] row_mask:0xf bank_mask:0xf
	v_mov_b32_dpp v223, v219 quad_perm:[1,0,3,2] row_mask:0xf bank_mask:0xf
	v_cndmask_b32_e64 v226, v222, v54, s[14:15]
	v_cndmask_b32_e64 v230, v38, v222, s[14:15]
	v_cndmask_b32_e64 v227, v223, v22, s[14:15]
	v_cndmask_b32_e64 v231, v6, v223, s[14:15]
	v_mul_f32_e32 v226, v226, v234
	v_mul_f32_e32 v230, v230, v238
	v_mul_f32_e32 v227, v227, v235
	v_mul_f32_e32 v231, v231, v239
	v_cvt_pk_bf16_f32 v226, v226, v230
	v_cvt_pk_bf16_f32 v227, v227, v231
	global_store_dword v[212:213], v226, off
	global_store_dword v[212:213], v227, off offset:128
	v_lshl_add_u64 v[214:215], v[212:213], 0, s[0:1]
	v_mul_f32_e32 v55, v55, v81
	v_mul_f32_e32 v39, v39, v81
	v_mul_f32_e32 v23, v23, v81
	v_mul_f32_e32 v7, v7, v81
	v_cndmask_b32_e64 v220, v55, v39, s[14:15]
	v_cndmask_b32_e64 v221, v23, v7, s[14:15]
	v_lshlrev_b32_e32 v236, 16, v142
	v_and_b32_e32 v240, 0xffff0000, v142
	v_lshlrev_b32_e32 v237, 16, v143
	v_and_b32_e32 v241, 0xffff0000, v143
	v_mov_b32_dpp v224, v220 quad_perm:[1,0,3,2] row_mask:0xf bank_mask:0xf
	v_mov_b32_dpp v225, v221 quad_perm:[1,0,3,2] row_mask:0xf bank_mask:0xf
	v_cndmask_b32_e64 v228, v224, v55, s[14:15]
	v_cndmask_b32_e64 v232, v39, v224, s[14:15]
	v_cndmask_b32_e64 v229, v225, v23, s[14:15]
	v_cndmask_b32_e64 v233, v7, v225, s[14:15]
	v_mul_f32_e32 v228, v228, v236
	v_mul_f32_e32 v232, v232, v240
	v_mul_f32_e32 v229, v229, v237
	v_mul_f32_e32 v233, v233, v241
	v_cvt_pk_bf16_f32 v228, v228, v232
	v_cvt_pk_bf16_f32 v229, v229, v233
	global_store_dword v[214:215], v228, off
	global_store_dword v[214:215], v229, off offset:128
	v_lshl_add_u64 v[212:213], v[214:215], 0, s[22:23]
	v_mul_f32_e32 v56, v56, v72
	v_mul_f32_e32 v40, v40, v72
	v_mul_f32_e32 v24, v24, v72
	v_mul_f32_e32 v8, v8, v72
	v_cndmask_b32_e64 v218, v56, v40, s[14:15]
	v_cndmask_b32_e64 v219, v24, v8, s[14:15]
	v_lshlrev_b32_e32 v234, 16, v146
	v_and_b32_e32 v238, 0xffff0000, v146
	v_lshlrev_b32_e32 v235, 16, v147
	v_and_b32_e32 v239, 0xffff0000, v147
	v_mov_b32_dpp v222, v218 quad_perm:[1,0,3,2] row_mask:0xf bank_mask:0xf
	v_mov_b32_dpp v223, v219 quad_perm:[1,0,3,2] row_mask:0xf bank_mask:0xf
	v_cndmask_b32_e64 v226, v222, v56, s[14:15]
	v_cndmask_b32_e64 v230, v40, v222, s[14:15]
	v_cndmask_b32_e64 v227, v223, v24, s[14:15]
	v_cndmask_b32_e64 v231, v8, v223, s[14:15]
	v_mul_f32_e32 v226, v226, v234
	v_mul_f32_e32 v230, v230, v238
	v_mul_f32_e32 v227, v227, v235
	v_mul_f32_e32 v231, v231, v239
	v_cvt_pk_bf16_f32 v226, v226, v230
	v_cvt_pk_bf16_f32 v227, v227, v231
	global_store_dword v[212:213], v226, off
	global_store_dword v[212:213], v227, off offset:128
	v_lshl_add_u64 v[214:215], v[212:213], 0, s[0:1]
	v_mul_f32_e32 v57, v57, v73
	v_mul_f32_e32 v41, v41, v73
	v_mul_f32_e32 v25, v25, v73
	v_mul_f32_e32 v9, v9, v73
	v_cndmask_b32_e64 v220, v57, v41, s[14:15]
	v_cndmask_b32_e64 v221, v25, v9, s[14:15]
	v_lshlrev_b32_e32 v236, 16, v148
	v_and_b32_e32 v240, 0xffff0000, v148
	v_lshlrev_b32_e32 v237, 16, v149
	v_and_b32_e32 v241, 0xffff0000, v149
	v_mov_b32_dpp v224, v220 quad_perm:[1,0,3,2] row_mask:0xf bank_mask:0xf
	v_mov_b32_dpp v225, v221 quad_perm:[1,0,3,2] row_mask:0xf bank_mask:0xf
	v_cndmask_b32_e64 v228, v224, v57, s[14:15]
	v_cndmask_b32_e64 v232, v41, v224, s[14:15]
	v_cndmask_b32_e64 v229, v225, v25, s[14:15]
	v_cndmask_b32_e64 v233, v9, v225, s[14:15]
	v_mul_f32_e32 v228, v228, v236
	v_mul_f32_e32 v232, v232, v240
	v_mul_f32_e32 v229, v229, v237
	v_mul_f32_e32 v233, v233, v241
	v_cvt_pk_bf16_f32 v228, v228, v232
	v_cvt_pk_bf16_f32 v229, v229, v233
	global_store_dword v[214:215], v228, off
	global_store_dword v[214:215], v229, off offset:128
	v_lshl_add_u64 v[212:213], v[214:215], 0, s[0:1]
	v_mul_f32_e32 v58, v58, v74
	v_mul_f32_e32 v42, v42, v74
	v_mul_f32_e32 v26, v26, v74
	v_mul_f32_e32 v10, v10, v74
	v_cndmask_b32_e64 v218, v58, v42, s[14:15]
	v_cndmask_b32_e64 v219, v26, v10, s[14:15]
	v_lshlrev_b32_e32 v234, 16, v150
	v_and_b32_e32 v238, 0xffff0000, v150
	v_lshlrev_b32_e32 v235, 16, v151
	v_and_b32_e32 v239, 0xffff0000, v151
	v_mov_b32_dpp v222, v218 quad_perm:[1,0,3,2] row_mask:0xf bank_mask:0xf
	v_mov_b32_dpp v223, v219 quad_perm:[1,0,3,2] row_mask:0xf bank_mask:0xf
	v_cndmask_b32_e64 v226, v222, v58, s[14:15]
	v_cndmask_b32_e64 v230, v42, v222, s[14:15]
	v_cndmask_b32_e64 v227, v223, v26, s[14:15]
	v_cndmask_b32_e64 v231, v10, v223, s[14:15]
	v_mul_f32_e32 v226, v226, v234
	v_mul_f32_e32 v230, v230, v238
	v_mul_f32_e32 v227, v227, v235
	v_mul_f32_e32 v231, v231, v239
	v_cvt_pk_bf16_f32 v226, v226, v230
; __device__ __forceinline__ unsigned cvtpk(float lo, float hi) { f32x2 v = {lo, hi}; bf16x2_t b = __builtin_convertvector(v, bf16x2_t); return __builtin_bit_cast(unsigned, b); }
; __device__ __forceinline__ float bf2f(bf16_t b) { return __uint_as_float(((unsigned)b) << 16); }
; __device__ __forceinline__ void retention_unit(LAS unsigned char* lds, const Args& a, int b, int hh, int qb, int wid, int lane) {
;     ...
;         for (int ii = 0; ii < 8; ++ii) { const int i = hh2 * 8 + ii; const size_t off = obase + (size_t)((i & 3) + 8 * (i >> 2)) * DM;
; #pragma unroll
;             for (int d = 0; d < 4; ++d) Qp[off + 32 * d] = (bf16_t)(cvtpk(O[d][i] * rs[i] * bf2f(gv[ii][d]), 0.f) & 0xffffu); }
;         asm volatile("" ::: "memory");
;     }
; __global__ void __launch_bounds__(512, 2) fwd_megakernel(Args a) {
;     ...
;         __syncthreads();
	v_cvt_pk_bf16_f32 v227, v227, v231
	global_store_dword v[212:213], v226, off
	global_store_dword v[212:213], v227, off offset:128
	v_lshl_add_u64 v[214:215], v[212:213], 0, s[0:1]
	v_mul_f32_e32 v59, v59, v76
	v_mul_f32_e32 v43, v43, v76
	v_mul_f32_e32 v27, v27, v76
	v_mul_f32_e32 v11, v11, v76
	v_cndmask_b32_e64 v220, v59, v43, s[14:15]
	v_cndmask_b32_e64 v221, v27, v11, s[14:15]
	v_lshlrev_b32_e32 v236, 16, v152
	v_and_b32_e32 v240, 0xffff0000, v152
	v_lshlrev_b32_e32 v237, 16, v153
	v_and_b32_e32 v241, 0xffff0000, v153
	v_mov_b32_dpp v224, v220 quad_perm:[1,0,3,2] row_mask:0xf bank_mask:0xf
	v_mov_b32_dpp v225, v221 quad_perm:[1,0,3,2] row_mask:0xf bank_mask:0xf
	v_cndmask_b32_e64 v228, v224, v59, s[14:15]
	v_cndmask_b32_e64 v232, v43, v224, s[14:15]
	v_cndmask_b32_e64 v229, v225, v27, s[14:15]
	v_cndmask_b32_e64 v233, v11, v225, s[14:15]
	v_mul_f32_e32 v228, v228, v236
	v_mul_f32_e32 v232, v232, v240
	v_mul_f32_e32 v229, v229, v237
	v_mul_f32_e32 v233, v233, v241
	v_cvt_pk_bf16_f32 v228, v228, v232
	v_cvt_pk_bf16_f32 v229, v229, v233
	global_store_dword v[214:215], v228, off
	global_store_dword v[214:215], v229, off offset:128
	v_lshl_add_u64 v[212:213], v[214:215], 0, s[22:23]
	v_mul_f32_e32 v60, v60, v83
	v_mul_f32_e32 v44, v44, v83
	v_mul_f32_e32 v28, v28, v83
	v_mul_f32_e32 v12, v12, v83
	v_cndmask_b32_e64 v218, v60, v44, s[14:15]
	v_cndmask_b32_e64 v219, v28, v12, s[14:15]
	v_lshlrev_b32_e32 v234, 16, v154
	v_and_b32_e32 v238, 0xffff0000, v154
	v_lshlrev_b32_e32 v235, 16, v155
	v_and_b32_e32 v239, 0xffff0000, v155
	v_mov_b32_dpp v222, v218 quad_perm:[1,0,3,2] row_mask:0xf bank_mask:0xf
	v_mov_b32_dpp v223, v219 quad_perm:[1,0,3,2] row_mask:0xf bank_mask:0xf
	v_cndmask_b32_e64 v226, v222, v60, s[14:15]
	v_cndmask_b32_e64 v230, v44, v222, s[14:15]
	v_cndmask_b32_e64 v227, v223, v28, s[14:15]
	v_cndmask_b32_e64 v231, v12, v223, s[14:15]
	v_mul_f32_e32 v226, v226, v234
	v_mul_f32_e32 v230, v230, v238
	v_mul_f32_e32 v227, v227, v235
	v_mul_f32_e32 v231, v231, v239
	v_cvt_pk_bf16_f32 v226, v226, v230
	v_cvt_pk_bf16_f32 v227, v227, v231
	global_store_dword v[212:213], v226, off
	global_store_dword v[212:213], v227, off offset:128
	v_lshl_add_u64 v[214:215], v[212:213], 0, s[0:1]
	v_mul_f32_e32 v61, v61, v82
	v_mul_f32_e32 v45, v45, v82
	v_mul_f32_e32 v29, v29, v82
	v_mul_f32_e32 v13, v13, v82
	v_cndmask_b32_e64 v220, v61, v45, s[14:15]
	v_cndmask_b32_e64 v221, v29, v13, s[14:15]
	v_lshlrev_b32_e32 v236, 16, v156
	v_and_b32_e32 v240, 0xffff0000, v156
	v_lshlrev_b32_e32 v237, 16, v157
	v_and_b32_e32 v241, 0xffff0000, v157
	v_mov_b32_dpp v224, v220 quad_perm:[1,0,3,2] row_mask:0xf bank_mask:0xf
	v_mov_b32_dpp v225, v221 quad_perm:[1,0,3,2] row_mask:0xf bank_mask:0xf
	v_cndmask_b32_e64 v228, v224, v61, s[14:15]
	v_cndmask_b32_e64 v232, v45, v224, s[14:15]
	v_cndmask_b32_e64 v229, v225, v29, s[14:15]
	v_cndmask_b32_e64 v233, v13, v225, s[14:15]
	v_mul_f32_e32 v228, v228, v236
	v_mul_f32_e32 v232, v232, v240
	v_mul_f32_e32 v229, v229, v237
	v_mul_f32_e32 v233, v233, v241
	v_cvt_pk_bf16_f32 v228, v228, v232
	v_cvt_pk_bf16_f32 v229, v229, v233
	global_store_dword v[214:215], v228, off
	global_store_dword v[214:215], v229, off offset:128
	v_lshl_add_u64 v[212:213], v[214:215], 0, s[0:1]
	v_mul_f32_e32 v62, v62, v80
	v_mul_f32_e32 v46, v46, v80
	v_mul_f32_e32 v30, v30, v80
	v_mul_f32_e32 v14, v14, v80
	v_cndmask_b32_e64 v218, v62, v46, s[14:15]
	v_cndmask_b32_e64 v219, v30, v14, s[14:15]
	v_lshlrev_b32_e32 v234, 16, v158
	v_and_b32_e32 v238, 0xffff0000, v158
	v_lshlrev_b32_e32 v235, 16, v159
	v_and_b32_e32 v239, 0xffff0000, v159
	v_mov_b32_dpp v222, v218 quad_perm:[1,0,3,2] row_mask:0xf bank_mask:0xf
	v_mov_b32_dpp v223, v219 quad_perm:[1,0,3,2] row_mask:0xf bank_mask:0xf
	v_cndmask_b32_e64 v226, v222, v62, s[14:15]
	v_cndmask_b32_e64 v230, v46, v222, s[14:15]
	v_cndmask_b32_e64 v227, v223, v30, s[14:15]
	v_cndmask_b32_e64 v231, v14, v223, s[14:15]
	v_mul_f32_e32 v226, v226, v234
	v_mul_f32_e32 v230, v230, v238
	v_mul_f32_e32 v227, v227, v235
	v_mul_f32_e32 v231, v231, v239
	v_cvt_pk_bf16_f32 v226, v226, v230
	v_cvt_pk_bf16_f32 v227, v227, v231
	global_store_dword v[212:213], v226, off
	global_store_dword v[212:213], v227, off offset:128
	v_lshl_add_u64 v[214:215], v[212:213], 0, s[0:1]
	v_mul_f32_e32 v63, v63, v78
	v_mul_f32_e32 v47, v47, v78
	v_mul_f32_e32 v31, v31, v78
	v_mul_f32_e32 v15, v15, v78
	v_cndmask_b32_e64 v220, v63, v47, s[14:15]
	v_cndmask_b32_e64 v221, v31, v15, s[14:15]
	v_lshlrev_b32_e32 v236, 16, v160
	v_and_b32_e32 v240, 0xffff0000, v160
	v_lshlrev_b32_e32 v237, 16, v161
	v_and_b32_e32 v241, 0xffff0000, v161
	v_mov_b32_dpp v224, v220 quad_perm:[1,0,3,2] row_mask:0xf bank_mask:0xf
	v_mov_b32_dpp v225, v221 quad_perm:[1,0,3,2] row_mask:0xf bank_mask:0xf
	v_cndmask_b32_e64 v228, v224, v63, s[14:15]
	v_cndmask_b32_e64 v232, v47, v224, s[14:15]
	v_cndmask_b32_e64 v229, v225, v31, s[14:15]
	v_cndmask_b32_e64 v233, v15, v225, s[14:15]
	v_mul_f32_e32 v228, v228, v236
	v_mul_f32_e32 v232, v232, v240
	v_mul_f32_e32 v229, v229, v237
	v_mul_f32_e32 v233, v233, v241
	v_cvt_pk_bf16_f32 v228, v228, v232
	v_cvt_pk_bf16_f32 v229, v229, v233
	global_store_dword v[214:215], v228, off
	global_store_dword v[214:215], v229, off offset:128
	s_barrier

; #define LAS __attribute__((address_space(3)))
; __device__ __forceinline__ void retention_unit(LAS unsigned char* lds, const Args& a, int b, int hh, int qb, int wid, int lane) {
;     ...
;     LAS float* xs = (LAS float*)(lds + LDS_XS);
;     float rs[16];
; #pragma unroll
;     for (int i = 0; i < 16; ++i) { float s = 0.f;
; #pragma unroll
;         for (int d = 0; d < 4; ++d) s += O[d][i] * O[d][i];
;         s += __shfl_xor(s, 1); s += __shfl_xor(s, 2); s += __shfl_xor(s, 4); s += __shfl_xor(s, 8); s += __shfl_xor(s, 16);
;         rs[i] = s; if (r == 0) xs[wid * 32 + (i & 3) + 8 * (i >> 2) + 4 * h] = s; }
;     __syncthreads();
; #pragma unroll
;     for (int i = 0; i < 16; ++i) { const float s = rs[i] + xs[(wid ^ 1) * 32 + (i & 3) + 8 * (i >> 2) + 4 * h]; rs[i] = 1.0f / sqrtf(s * (1.0f / 256.0f) + EPS); }
;     const size_t obase = (size_t)(b * SEQ + qb * 128 + rg * 32 + 4 * h) * DM + hh * 256 + hf * 128 + r;
; #pragma unroll
;     for (int hh2 = 0; hh2 < 2; ++hh2) {
;         bf16_t gv[8][4];
; #pragma unroll
;         for (int ii = 0; ii < 8; ++ii) { const int i = hh2 * 8 + ii; const size_t off = obase + (size_t)((i & 3) + 8 * (i >> 2)) * DM;
; #pragma unroll
;             for (int d = 0; d < 4; ++d) gv[ii][d] = Gp[off + 32 * d]; }
.LBB0_689:
	s_add_i32 s0, s42, s41
	v_add_u32_e32 v210, s0, v209
	v_ashrrev_i32_e32 v211, 31, v210
	v_lshlrev_b64 v[210:211], 11, v[210:211]
	v_lshl_add_u64 v[210:211], v[210:211], 0, s[46:47]
	v_or_b32_e32 v210, s78, v210
	v_or_b32_e32 v210, v210, v208
	v_readlane_b32 s0, v242, 30
	v_lshlrev_b64 v[210:211], 1, v[210:211]
	v_readlane_b32 s1, v242, 31
	s_movk_i32 s14, 0x1000
	s_mov_b32 s15, 0
	s_movk_i32 s22, 0x5000
	s_mov_b32 s23, 0
	v_and_b32_e32 v216, 1, v208
	v_mul_u32_u24_e32 v216, 62, v216
	v_mov_b32_e32 v217, 0
	v_lshl_add_u64 v[210:211], s[0:1], 0, v[210:211]
	v_lshl_add_u64 v[210:211], v[210:211], 0, v[216:217]
	global_load_dword v128, v[210:211], off
	global_load_dword v129, v[210:211], off offset:128
	v_lshl_add_u64 v[214:215], v[210:211], 0, s[14:15]
	global_load_dword v130, v[214:215], off
	global_load_dword v131, v[214:215], off offset:128
	v_lshl_add_u64 v[212:213], v[214:215], 0, s[14:15]
	global_load_dword v132, v[212:213], off
	global_load_dword v133, v[212:213], off offset:128
	v_lshl_add_u64 v[214:215], v[212:213], 0, s[14:15]
	global_load_dword v134, v[214:215], off
	global_load_dword v135, v[214:215], off offset:128
	v_lshl_add_u64 v[212:213], v[214:215], 0, s[22:23]
	global_load_dword v136, v[212:213], off
	global_load_dword v137, v[212:213], off offset:128
	v_lshl_add_u64 v[214:215], v[212:213], 0, s[14:15]
	global_load_dword v138, v[214:215], off
	global_load_dword v139, v[214:215], off offset:128
	v_lshl_add_u64 v[212:213], v[214:215], 0, s[14:15]
	global_load_dword v140, v[212:213], off
	global_load_dword v141, v[212:213], off offset:128
	v_lshl_add_u64 v[214:215], v[212:213], 0, s[14:15]
	global_load_dword v142, v[214:215], off
	global_load_dword v143, v[214:215], off offset:128
	v_lshl_add_u64 v[212:213], v[214:215], 0, s[22:23]
	global_load_dword v146, v[212:213], off
	global_load_dword v147, v[212:213], off offset:128
	v_lshl_add_u64 v[214:215], v[212:213], 0, s[14:15]
	global_load_dword v148, v[214:215], off
	global_load_dword v149, v[214:215], off offset:128
	v_lshl_add_u64 v[212:213], v[214:215], 0, s[14:15]
	global_load_dword v150, v[212:213], off
	global_load_dword v151, v[212:213], off offset:128
	v_lshl_add_u64 v[214:215], v[212:213], 0, s[14:15]
	global_load_dword v152, v[214:215], off
	global_load_dword v153, v[214:215], off offset:128
	v_lshl_add_u64 v[212:213], v[214:215], 0, s[22:23]
	global_load_dword v154, v[212:213], off
	global_load_dword v155, v[212:213], off offset:128
	v_lshl_add_u64 v[214:215], v[212:213], 0, s[14:15]
	global_load_dword v156, v[214:215], off
	global_load_dword v157, v[214:215], off offset:128
	v_lshl_add_u64 v[212:213], v[214:215], 0, s[14:15]
	global_load_dword v158, v[212:213], off
	global_load_dword v159, v[212:213], off offset:128
	v_lshl_add_u64 v[214:215], v[212:213], 0, s[14:15]
	global_load_dword v160, v[214:215], off
	global_load_dword v161, v[214:215], off offset:128
	v_mul_f32_e32 v88, v32, v32
	v_fmac_f32_e32 v88, v48, v48
	v_fmac_f32_e32 v88, v16, v16
	v_fmac_f32_e32 v88, v0, v0
	v_mul_f32_e32 v87, v33, v33
	v_fmac_f32_e32 v87, v49, v49
	v_fmac_f32_e32 v87, v17, v17
	v_fmac_f32_e32 v87, v1, v1
	v_mul_f32_e32 v86, v34, v34
	v_fmac_f32_e32 v86, v50, v50
	v_fmac_f32_e32 v86, v18, v18
	v_fmac_f32_e32 v86, v2, v2
	v_mul_f32_e32 v85, v35, v35
	v_fmac_f32_e32 v85, v51, v51
	v_fmac_f32_e32 v85, v19, v19
	v_fmac_f32_e32 v85, v3, v3
	v_mul_f32_e32 v75, v36, v36
	v_fmac_f32_e32 v75, v52, v52
	v_fmac_f32_e32 v75, v20, v20
	v_fmac_f32_e32 v75, v4, v4
	v_mul_f32_e32 v77, v37, v37
	v_fmac_f32_e32 v77, v53, v53
	v_fmac_f32_e32 v77, v21, v21
	v_fmac_f32_e32 v77, v5, v5
	v_mul_f32_e32 v79, v38, v38
	v_fmac_f32_e32 v79, v54, v54
	v_fmac_f32_e32 v79, v22, v22
	v_fmac_f32_e32 v79, v6, v6
	v_mul_f32_e32 v81, v39, v39
	v_fmac_f32_e32 v81, v55, v55
	v_fmac_f32_e32 v81, v23, v23
	v_fmac_f32_e32 v81, v7, v7
	v_mul_f32_e32 v72, v40, v40
	v_fmac_f32_e32 v72, v56, v56
	v_fmac_f32_e32 v72, v24, v24
	v_fmac_f32_e32 v72, v8, v8
	v_mul_f32_e32 v73, v41, v41
	v_fmac_f32_e32 v73, v57, v57
	v_fmac_f32_e32 v73, v25, v25
	v_fmac_f32_e32 v73, v9, v9
	v_mul_f32_e32 v74, v42, v42
	v_fmac_f32_e32 v74, v58, v58
	v_fmac_f32_e32 v74, v26, v26
	v_fmac_f32_e32 v74, v10, v10
	v_mul_f32_e32 v76, v43, v43
	v_fmac_f32_e32 v76, v59, v59
	v_fmac_f32_e32 v76, v27, v27
	v_fmac_f32_e32 v76, v11, v11
	v_mul_f32_e32 v83, v44, v44
	v_fmac_f32_e32 v83, v60, v60
	v_fmac_f32_e32 v83, v28, v28
	v_fmac_f32_e32 v83, v12, v12
	v_mul_f32_e32 v82, v45, v45
	v_fmac_f32_e32 v82, v61, v61
	v_fmac_f32_e32 v82, v29, v29
	v_fmac_f32_e32 v82, v13, v13
	v_mul_f32_e32 v80, v46, v46
	v_fmac_f32_e32 v80, v62, v62
	v_fmac_f32_e32 v80, v30, v30
	v_fmac_f32_e32 v80, v14, v14
	v_mul_f32_e32 v78, v47, v47
	v_fmac_f32_e32 v78, v63, v63
	v_fmac_f32_e32 v78, v31, v31
	v_fmac_f32_e32 v78, v15, v15
	v_xor_b32_e32 v218, 1, v202
	v_lshlrev_b32_e32 v218, 2, v218
	v_xor_b32_e32 v219, 2, v202
	v_lshlrev_b32_e32 v219, 2, v219
	v_xor_b32_e32 v220, 4, v202
	v_lshlrev_b32_e32 v220, 2, v220
	v_xor_b32_e32 v221, 8, v202
	v_lshlrev_b32_e32 v221, 2, v221
	v_xor_b32_e32 v222, 16, v202
	v_lshlrev_b32_e32 v222, 2, v222
	ds_bpermute_b32 v223, v218, v88
	ds_bpermute_b32 v224, v218, v87
	ds_bpermute_b32 v225, v218, v86
	ds_bpermute_b32 v226, v218, v85
	ds_bpermute_b32 v227, v218, v75
	ds_bpermute_b32 v228, v218, v77
	ds_bpermute_b32 v229, v218, v79
	ds_bpermute_b32 v230, v218, v81
	ds_bpermute_b32 v231, v218, v72
	ds_bpermute_b32 v232, v218, v73
	ds_bpermute_b32 v233, v218, v74
	ds_bpermute_b32 v234, v218, v76
	ds_bpermute_b32 v235, v218, v83
	ds_bpermute_b32 v236, v218, v82
	ds_bpermute_b32 v237, v218, v80
	ds_bpermute_b32 v238, v218, v78
	s_waitcnt lgkmcnt(8)
; __device__ __forceinline__ void retention_unit(LAS unsigned char* lds, const Args& a, int b, int hh, int qb, int wid, int lane) {
;     ...
;     for (int i = 0; i < 16; ++i) { float s = 0.f;
; #pragma unroll
;         for (int d = 0; d < 4; ++d) s += O[d][i] * O[d][i];
;         s += __shfl_xor(s, 1); s += __shfl_xor(s, 2); s += __shfl_xor(s, 4); s += __shfl_xor(s, 8); s += __shfl_xor(s, 16);
;         rs[i] = s; if (r == 0) xs[wid * 32 + (i & 3) + 8 * (i >> 2) + 4 * h] = s; }
;     __syncthreads();
	v_add_f32_e32 v88, v88, v223
	v_add_f32_e32 v87, v87, v224
	v_add_f32_e32 v86, v86, v225
	v_add_f32_e32 v85, v85, v226
	v_add_f32_e32 v75, v75, v227
	v_add_f32_e32 v77, v77, v228
	v_add_f32_e32 v79, v79, v229
	v_add_f32_e32 v81, v81, v230
	ds_bpermute_b32 v223, v219, v88
	ds_bpermute_b32 v224, v219, v87
	ds_bpermute_b32 v225, v219, v86
	ds_bpermute_b32 v226, v219, v85
	ds_bpermute_b32 v227, v219, v75
	ds_bpermute_b32 v228, v219, v77
	ds_bpermute_b32 v229, v219, v79
	ds_bpermute_b32 v230, v219, v81
	s_waitcnt lgkmcnt(8)
	v_add_f32_e32 v72, v72, v231
	v_add_f32_e32 v73, v73, v232
	v_add_f32_e32 v74, v74, v233
	v_add_f32_e32 v76, v76, v234
	v_add_f32_e32 v83, v83, v235
	v_add_f32_e32 v82, v82, v236
	v_add_f32_e32 v80, v80, v237
	v_add_f32_e32 v78, v78, v238
	ds_bpermute_b32 v231, v219, v72
	ds_bpermute_b32 v232, v219, v73
	ds_bpermute_b32 v233, v219, v74
	ds_bpermute_b32 v234, v219, v76
	ds_bpermute_b32 v235, v219, v83
	ds_bpermute_b32 v236, v219, v82
	ds_bpermute_b32 v237, v219, v80
	ds_bpermute_b32 v238, v219, v78
	s_waitcnt lgkmcnt(8)
	v_add_f32_e32 v88, v88, v223
	v_add_f32_e32 v87, v87, v224
	v_add_f32_e32 v86, v86, v225
	v_add_f32_e32 v85, v85, v226
	v_add_f32_e32 v75, v75, v227
	v_add_f32_e32 v77, v77, v228
	v_add_f32_e32 v79, v79, v229
	v_add_f32_e32 v81, v81, v230
	ds_bpermute_b32 v223, v220, v88
	ds_bpermute_b32 v224, v220, v87
	ds_bpermute_b32 v225, v220, v86
	ds_bpermute_b32 v226, v220, v85
	ds_bpermute_b32 v227, v220, v75
	ds_bpermute_b32 v228, v220, v77
	ds_bpermute_b32 v229, v220, v79
	ds_bpermute_b32 v230, v220, v81
	s_waitcnt lgkmcnt(8)
	v_add_f32_e32 v72, v72, v231
	v_add_f32_e32 v73, v73, v232
	v_add_f32_e32 v74, v74, v233
	v_add_f32_e32 v76, v76, v234
	v_add_f32_e32 v83, v83, v235
	v_add_f32_e32 v82, v82, v236
	v_add_f32_e32 v80, v80, v237
	v_add_f32_e32 v78, v78, v238
	ds_bpermute_b32 v231, v220, v72
	ds_bpermute_b32 v232, v220, v73
	ds_bpermute_b32 v233, v220, v74
	ds_bpermute_b32 v234, v220, v76
	ds_bpermute_b32 v235, v220, v83
	ds_bpermute_b32 v236, v220, v82
	ds_bpermute_b32 v237, v220, v80
	ds_bpermute_b32 v238, v220, v78
	s_waitcnt lgkmcnt(8)
	v_add_f32_e32 v88, v88, v223
	v_add_f32_e32 v87, v87, v224
	v_add_f32_e32 v86, v86, v225
	v_add_f32_e32 v85, v85, v226
	v_add_f32_e32 v75, v75, v227
	v_add_f32_e32 v77, v77, v228
	v_add_f32_e32 v79, v79, v229
	v_add_f32_e32 v81, v81, v230
	ds_bpermute_b32 v223, v221, v88
	ds_bpermute_b32 v224, v221, v87
	ds_bpermute_b32 v225, v221, v86
	ds_bpermute_b32 v226, v221, v85
	ds_bpermute_b32 v227, v221, v75
	ds_bpermute_b32 v228, v221, v77
	ds_bpermute_b32 v229, v221, v79
	ds_bpermute_b32 v230, v221, v81
	s_waitcnt lgkmcnt(8)
	v_add_f32_e32 v72, v72, v231
	v_add_f32_e32 v73, v73, v232
	v_add_f32_e32 v74, v74, v233
	v_add_f32_e32 v76, v76, v234
	v_add_f32_e32 v83, v83, v235
	v_add_f32_e32 v82, v82, v236
	v_add_f32_e32 v80, v80, v237
	v_add_f32_e32 v78, v78, v238
	ds_bpermute_b32 v231, v221, v72
	ds_bpermute_b32 v232, v221, v73
	ds_bpermute_b32 v233, v221, v74
	ds_bpermute_b32 v234, v221, v76
	ds_bpermute_b32 v235, v221, v83
	ds_bpermute_b32 v236, v221, v82
	ds_bpermute_b32 v237, v221, v80
	ds_bpermute_b32 v238, v221, v78
	s_waitcnt lgkmcnt(8)
	v_add_f32_e32 v88, v88, v223
	v_add_f32_e32 v87, v87, v224
	v_add_f32_e32 v86, v86, v225
	v_add_f32_e32 v85, v85, v226
	v_add_f32_e32 v75, v75, v227
	v_add_f32_e32 v77, v77, v228
	v_add_f32_e32 v79, v79, v229
	v_add_f32_e32 v81, v81, v230
	ds_bpermute_b32 v223, v222, v88
	ds_bpermute_b32 v224, v222, v87
	ds_bpermute_b32 v225, v222, v86
	ds_bpermute_b32 v226, v222, v85
	ds_bpermute_b32 v227, v222, v75
	ds_bpermute_b32 v228, v222, v77
	ds_bpermute_b32 v229, v222, v79
	ds_bpermute_b32 v230, v222, v81
	s_waitcnt lgkmcnt(8)
	v_add_f32_e32 v72, v72, v231
	v_add_f32_e32 v73, v73, v232
	v_add_f32_e32 v74, v74, v233
	v_add_f32_e32 v76, v76, v234
	v_add_f32_e32 v83, v83, v235
	v_add_f32_e32 v82, v82, v236
	v_add_f32_e32 v80, v80, v237
	v_add_f32_e32 v78, v78, v238
	ds_bpermute_b32 v231, v222, v72
	ds_bpermute_b32 v232, v222, v73
	ds_bpermute_b32 v233, v222, v74
	ds_bpermute_b32 v234, v222, v76
	ds_bpermute_b32 v235, v222, v83
	ds_bpermute_b32 v236, v222, v82
	ds_bpermute_b32 v237, v222, v80
	ds_bpermute_b32 v238, v222, v78
	s_waitcnt lgkmcnt(8)
	v_add_f32_e32 v88, v88, v223
	v_add_f32_e32 v87, v87, v224
	v_add_f32_e32 v86, v86, v225
	v_add_f32_e32 v85, v85, v226
	v_add_f32_e32 v75, v75, v227
	v_add_f32_e32 v77, v77, v228
	v_add_f32_e32 v79, v79, v229
	v_add_f32_e32 v81, v81, v230
	s_waitcnt lgkmcnt(0)
	v_add_f32_e32 v72, v72, v231
	v_add_f32_e32 v73, v73, v232
	v_add_f32_e32 v74, v74, v233
	v_add_f32_e32 v76, v76, v234
	v_add_f32_e32 v83, v83, v235
	v_add_f32_e32 v82, v82, v236
	v_add_f32_e32 v80, v80, v237
	v_add_f32_e32 v78, v78, v238
	v_cmp_eq_u32_e32 vcc, 0, v208
	v_lshl_add_u32 v68, v209, 2, s77
	s_nop 3
	s_and_saveexec_b64 s[0:1], vcc
	ds_write_b32 v68, v88
	ds_write_b32 v68, v87 offset:4
	ds_write_b32 v68, v86 offset:8
	ds_write_b32 v68, v85 offset:12
	ds_write_b32 v68, v75 offset:32
	ds_write_b32 v68, v77 offset:36
	ds_write_b32 v68, v79 offset:40
	ds_write_b32 v68, v81 offset:44
	ds_write_b32 v68, v72 offset:64
	ds_write_b32 v68, v73 offset:68
	ds_write_b32 v68, v74 offset:72
	ds_write_b32 v68, v76 offset:76
	ds_write_b32 v68, v83 offset:96
	ds_write_b32 v68, v82 offset:100
	ds_write_b32 v68, v80 offset:104
	ds_write_b32 v68, v78 offset:108
	s_branch .LBB0_648
